# attention: next half-tile's score-accumulator init hoisted before the staging barriers (on top of the reschedule)
# speedup vs baseline: 1.0078x; 1.0078x over previous
; __device__ __forceinline__ void qk_fin(f32x16& n0, f32x16& n1, const char* Ks, const bf16x8* qr, int r32, int hi, int cbase,
;                                        const f32x16& q0, const f32x16& q1, float& l_reg, bf16x8& pa0, bf16x8& pa1, bf16x8& pa2, bf16x8& pa3) {
;   float ps = 0.f;
;   { const bf16x8 k0 = KFRAG(0, 0), k1 = KFRAG(0, 1); n0 = __builtin_amdgcn_mfma_f32_32x32x16_bf16(k0, qr[0], n0, 0, 0, 0); n1 = __builtin_amdgcn_mfma_f32_32x32x16_bf16(k1, qr[0], n1, 0, 0, 0); }
; #pragma unroll
;   for (int r = 0; r < 8; ++r) ps += q0[r];
;   PK4(q0, 0, pa0); asm volatile("" : "+v"(pa0), "+v"(ps)); SBAR();
;   { const bf16x8 k0 = KFRAG(1, 0), k1 = KFRAG(1, 1); n0 = __builtin_amdgcn_mfma_f32_32x32x16_bf16(k0, qr[1], n0, 0, 0, 0); n1 = __builtin_amdgcn_mfma_f32_32x32x16_bf16(k1, qr[1], n1, 0, 0, 0); }
; #pragma unroll
;   for (int r = 8; r < 16; ++r) ps += q0[r];
;   PK4(q0, 8, pa1); asm volatile("" : "+v"(pa1), "+v"(ps)); SBAR();
;   { const bf16x8 k0 = KFRAG(2, 0), k1 = KFRAG(2, 1); n0 = __builtin_amdgcn_mfma_f32_32x32x16_bf16(k0, qr[2], n0, 0, 0, 0); n1 = __builtin_amdgcn_mfma_f32_32x32x16_bf16(k1, qr[2], n1, 0, 0, 0); }
; #pragma unroll
;   for (int r = 0; r < 8; ++r) ps += q1[r];
;   PK4(q1, 0, pa2); asm volatile("" : "+v"(pa2), "+v"(ps)); SBAR();
;   { const bf16x8 k0 = KFRAG(3, 0), k1 = KFRAG(3, 1); n0 = __builtin_amdgcn_mfma_f32_32x32x16_bf16(k0, qr[3], n0, 0, 0, 0); n1 = __builtin_amdgcn_mfma_f32_32x32x16_bf16(k1, qr[3], n1, 0, 0, 0); }
; #pragma unroll
;   for (int r = 8; r < 16; ++r) ps += q1[r];
;   PK4(q1, 8, pa3);
;   { auto rr = __builtin_amdgcn_permlane32_swap(__float_as_uint(ps), __float_as_uint(ps), false, false); ps = __uint_as_float(rr[0]) + __uint_as_float(rr[1]); }
;   l_reg += ps; SBAR();
; }
; template <int D0> __device__ __forceinline__ void pv_one(f32x16& od, int vb, bf16x8 pa0, bf16x8 pa1, bf16x8 pa2, bf16x8 pa3) {
;   const s16x4 l0 = tr_read<v_rd_off(D0, 0, 0)>(vb), h0 = tr_read<v_rd_off(D0, 0, 1)>(vb), l1 = tr_read<v_rd_off(D0, 1, 0)>(vb), h1 = tr_read<v_rd_off(D0, 1, 1)>(vb);
;   const s16x4 l2 = tr_read<v_rd_off(D0, 2, 0)>(vb), h2 = tr_read<v_rd_off(D0, 2, 1)>(vb), l3 = tr_read<v_rd_off(D0, 3, 0)>(vb), h3 = tr_read<v_rd_off(D0, 3, 1)>(vb);
;   asm volatile("s_waitcnt lgkmcnt(0)" ::: "memory"); SBAR();
;     ...
;   od = __builtin_amdgcn_mfma_f32_32x32x16_bf16(pa0, PK(l0, h0), od, 0, 0, 0);
.LBB0_326:
	ds_read_b128 v[248:251], v241 offset:49152
	ds_read_b128 v[214:217], v241 offset:57344
	v_add_f32_e32 v179, 0, v80
	v_add_f32_e32 v179, v81, v179
	v_cvt_pk_bf16_f32 v80, v80, v81
	v_add_f32_e32 v179, v82, v179
	v_add_f32_e32 v179, v83, v179
	v_cvt_pk_bf16_f32 v81, v82, v83
	v_add_f32_e32 v179, v84, v179
	v_add_f32_e32 v179, v85, v179
	v_cvt_pk_bf16_f32 v82, v84, v85
	v_add_f32_e32 v179, v86, v179
	v_add_f32_e32 v179, v87, v179
	v_cvt_pk_bf16_f32 v83, v86, v87
	s_nop 1
	v_permlane32_swap_b32_e32 v80, v82
	v_permlane32_swap_b32_e32 v81, v83
	s_waitcnt lgkmcnt(1)
	v_mfma_f32_32x32x16_bf16 v[112:127], v[248:251], v[132:135], v[112:127]
	s_waitcnt lgkmcnt(0)
	v_mfma_f32_32x32x16_bf16 v[96:111], v[214:217], v[132:135], v[96:111]
	ds_read_b128 v[248:251], v242 offset:49152
	ds_read_b128 v[214:217], v242 offset:57344
	v_add_f32_e32 v179, v88, v179
	v_add_f32_e32 v179, v89, v179
	v_cvt_pk_bf16_f32 v84, v88, v89
	v_add_f32_e32 v179, v90, v179
	v_add_f32_e32 v179, v91, v179
	v_cvt_pk_bf16_f32 v85, v90, v91
	v_add_f32_e32 v179, v92, v179
	v_add_f32_e32 v179, v93, v179
	v_cvt_pk_bf16_f32 v86, v92, v93
	v_add_f32_e32 v179, v94, v179
	v_add_f32_e32 v179, v95, v179
	v_cvt_pk_bf16_f32 v87, v94, v95
	s_nop 1
	v_permlane32_swap_b32_e32 v84, v86
	v_permlane32_swap_b32_e32 v85, v87
	s_waitcnt lgkmcnt(1)
	v_mfma_f32_32x32x16_bf16 v[112:127], v[248:251], v[128:131], v[112:127]
	s_waitcnt lgkmcnt(0)
	v_mfma_f32_32x32x16_bf16 v[96:111], v[214:217], v[128:131], v[96:111]
	ds_read_b128 v[248:251], v243 offset:49152
	ds_read_b128 v[214:217], v243 offset:57344
	v_add_f32_e32 v179, v64, v179
	v_add_f32_e32 v179, v65, v179
	v_cvt_pk_bf16_f32 v64, v64, v65
	v_add_f32_e32 v179, v66, v179
	v_add_f32_e32 v179, v67, v179
	v_cvt_pk_bf16_f32 v65, v66, v67
	v_add_f32_e32 v179, v68, v179
	v_add_f32_e32 v179, v69, v179
	v_cvt_pk_bf16_f32 v66, v68, v69
	v_add_f32_e32 v179, v70, v179
	v_add_f32_e32 v179, v71, v179
	v_cvt_pk_bf16_f32 v67, v70, v71
	s_nop 1
	v_permlane32_swap_b32_e32 v64, v66
	v_permlane32_swap_b32_e32 v65, v67
	s_waitcnt lgkmcnt(1)
	v_mfma_f32_32x32x16_bf16 v[112:127], v[248:251], v[140:143], v[112:127]
	s_waitcnt lgkmcnt(0)
	v_mfma_f32_32x32x16_bf16 v[96:111], v[214:217], v[140:143], v[96:111]
	ds_read_b128 v[248:251], v244 offset:49152
	ds_read_b128 v[214:217], v244 offset:57344
	v_add_f32_e32 v179, v72, v179
	v_add_f32_e32 v179, v73, v179
	v_cvt_pk_bf16_f32 v68, v72, v73
	v_add_f32_e32 v179, v74, v179
	v_add_f32_e32 v179, v75, v179
	v_cvt_pk_bf16_f32 v69, v74, v75
	v_add_f32_e32 v179, v76, v179
	v_add_f32_e32 v179, v77, v179
	v_cvt_pk_bf16_f32 v70, v76, v77
	v_add_f32_e32 v179, v78, v179
	v_add_f32_e32 v247, v79, v179
	v_cvt_pk_bf16_f32 v71, v78, v79
	s_nop 1
	v_permlane32_swap_b32_e32 v68, v70
	v_permlane32_swap_b32_e32 v69, v71
	s_waitcnt lgkmcnt(1)
	v_mfma_f32_32x32x16_bf16 v[112:127], v[248:251], v[136:139], v[112:127]
	s_waitcnt lgkmcnt(0)
	v_mfma_f32_32x32x16_bf16 v[96:111], v[214:217], v[136:139], v[96:111]
	v_mov_b32_e32 v248, v247
	s_nop 1
	v_permlane32_swap_b32_e32 v247, v248
	ds_read_b64_tr_b16 v[72:73], v230 offset:0
	ds_read_b64_tr_b16 v[74:75], v230 offset:2048
	ds_read_b64_tr_b16 v[76:77], v230 offset:4096
	ds_read_b64_tr_b16 v[78:79], v230 offset:6144
	ds_read_b64_tr_b16 v[88:89], v230 offset:8192
	ds_read_b64_tr_b16 v[90:91], v230 offset:10240
	ds_read_b64_tr_b16 v[92:93], v230 offset:12288
	ds_read_b64_tr_b16 v[94:95], v230 offset:14336
	s_waitcnt lgkmcnt(4)
	v_mfma_f32_32x32x16_bf16 v[48:63], v[80:83], v[72:75], v[48:63]
	v_exp_f32_e32 v112, v112
	v_exp_f32_e32 v113, v113
	v_mfma_f32_32x32x16_bf16 v[48:63], v[84:87], v[76:79], v[48:63]
	ds_read_b64_tr_b16 v[72:73], v230 offset:512
	ds_read_b64_tr_b16 v[74:75], v230 offset:2560
	ds_read_b64_tr_b16 v[76:77], v230 offset:4608
	ds_read_b64_tr_b16 v[78:79], v230 offset:6656
	v_exp_f32_e32 v114, v114
	v_exp_f32_e32 v115, v115
	s_waitcnt lgkmcnt(4)
	v_mfma_f32_32x32x16_bf16 v[48:63], v[64:67], v[88:91], v[48:63]
	v_exp_f32_e32 v116, v116
	v_exp_f32_e32 v117, v117
	v_mfma_f32_32x32x16_bf16 v[48:63], v[68:71], v[92:95], v[48:63]
	ds_read_b64_tr_b16 v[88:89], v230 offset:8704
	ds_read_b64_tr_b16 v[90:91], v230 offset:10752
	ds_read_b64_tr_b16 v[92:93], v230 offset:12800
	ds_read_b64_tr_b16 v[94:95], v230 offset:14848
	v_exp_f32_e32 v118, v118
	v_exp_f32_e32 v119, v119
	s_waitcnt lgkmcnt(4)
	v_mfma_f32_32x32x16_bf16 v[32:47], v[80:83], v[72:75], v[32:47]
	v_exp_f32_e32 v120, v120
	v_exp_f32_e32 v121, v121
	v_mfma_f32_32x32x16_bf16 v[32:47], v[84:87], v[76:79], v[32:47]
	ds_read_b64_tr_b16 v[72:73], v230 offset:1024
	ds_read_b64_tr_b16 v[74:75], v230 offset:3072
	ds_read_b64_tr_b16 v[76:77], v230 offset:5120
	ds_read_b64_tr_b16 v[78:79], v230 offset:7168
	v_exp_f32_e32 v122, v122
	v_exp_f32_e32 v123, v123
	s_waitcnt lgkmcnt(4)
	v_mfma_f32_32x32x16_bf16 v[32:47], v[64:67], v[88:91], v[32:47]
	v_exp_f32_e32 v124, v124
	v_exp_f32_e32 v125, v125
	v_mfma_f32_32x32x16_bf16 v[32:47], v[68:71], v[92:95], v[32:47]
	ds_read_b64_tr_b16 v[88:89], v230 offset:9216
	ds_read_b64_tr_b16 v[90:91], v230 offset:11264
	ds_read_b64_tr_b16 v[92:93], v230 offset:13312
	ds_read_b64_tr_b16 v[94:95], v230 offset:15360
	v_exp_f32_e32 v126, v126
	v_exp_f32_e32 v127, v127
	s_waitcnt lgkmcnt(4)
	v_mfma_f32_32x32x16_bf16 v[16:31], v[80:83], v[72:75], v[16:31]
	v_exp_f32_e32 v96, v96
	v_exp_f32_e32 v97, v97
	v_mfma_f32_32x32x16_bf16 v[16:31], v[84:87], v[76:79], v[16:31]
	ds_read_b64_tr_b16 v[72:73], v230 offset:1536
	ds_read_b64_tr_b16 v[74:75], v230 offset:3584
	ds_read_b64_tr_b16 v[76:77], v230 offset:5632
	ds_read_b64_tr_b16 v[78:79], v230 offset:7680
	v_exp_f32_e32 v98, v98
	v_exp_f32_e32 v99, v99
	s_waitcnt lgkmcnt(4)
	v_mfma_f32_32x32x16_bf16 v[16:31], v[64:67], v[88:91], v[16:31]
	v_exp_f32_e32 v100, v100
	v_exp_f32_e32 v101, v101
	v_mfma_f32_32x32x16_bf16 v[16:31], v[68:71], v[92:95], v[16:31]
	ds_read_b64_tr_b16 v[88:89], v230 offset:9728
	ds_read_b64_tr_b16 v[90:91], v230 offset:11776
	ds_read_b64_tr_b16 v[92:93], v230 offset:13824
	ds_read_b64_tr_b16 v[94:95], v230 offset:15872
	v_exp_f32_e32 v102, v102
	v_exp_f32_e32 v103, v103
	s_waitcnt lgkmcnt(4)
	v_mfma_f32_32x32x16_bf16 v[0:15], v[80:83], v[72:75], v[0:15]
	v_exp_f32_e32 v104, v104
	v_exp_f32_e32 v105, v105
	v_mfma_f32_32x32x16_bf16 v[0:15], v[84:87], v[76:79], v[0:15]
	v_exp_f32_e32 v106, v106
	v_exp_f32_e32 v107, v107
	s_waitcnt lgkmcnt(0)
	v_mfma_f32_32x32x16_bf16 v[0:15], v[64:67], v[88:91], v[0:15]
	v_exp_f32_e32 v108, v108
	v_exp_f32_e32 v109, v109
	v_mfma_f32_32x32x16_bf16 v[0:15], v[68:71], v[92:95], v[0:15]
	v_exp_f32_e32 v110, v110
	v_exp_f32_e32 v111, v111
	s_add_i32 s6, s33, -1
	s_cmp_ge_u32 s6, s73
	v_cvt_f32_i32_e32 v65, s33
	s_cselect_b64 s[6:7], -1, 0
	s_cmp_ge_u32 s33, s72
	v_cndmask_b32_e64 v64, 0, -1, s[6:7]
	s_cselect_b64 vcc, -1, 0
	v_cndmask_b32_e32 v64, 1, v64, vcc
	v_cmp_ne_u32_e32 vcc, 0, v64
	v_fmamk_f32 v208, v65, 0xc2800000, v184
	s_cbranch_vccz .Lattn_i2_ovl
; __device__ __forceinline__ void sc_init(f32x16& p0, f32x16& p1, float dq, float nsl2, float m_ref, int side) {
;   if (side != 0) { const float sg = (float)side; const float base0 = fmaf(sg * nsl2, dq, -m_ref), base1 = base0 - sg * 32.f * nsl2;
; #pragma unroll
;     for (int r = 0; r < 16; ++r) { const float c = -sg * nsl2 * (float)((r & 3) + 8 * (r >> 2)); p0[r] = base0 + c; p1[r] = base1 + c; }
;   } else {
	v_cvt_f32_i32_e32 v64, v64
	v_mul_f32_e32 v66, v180, v64
	v_mul_f32_e32 v65, 0x42000000, v64
	v_xor_b32_e32 v64, 0x80000000, v64
	v_fma_f32 v179, v66, v208, -v182
	v_pk_mul_f32 v[214:215], v[188:189], v[64:65]
	v_pk_fma_f32 v[216:217], v[188:189], v[64:65], v[178:179] neg_lo:[1,0,0] neg_hi:[1,0,0]
	v_mul_f32_e32 v80, 0, v214
	v_pk_mul_f32 v[82:83], v[214:215], s[14:15]
	v_mov_b32_e32 v81, v214
	v_pk_add_f32 v[64:65], v[80:81], v[216:217] op_sel:[0,1]
	v_pk_fma_f32 v[66:67], v[214:215], s[48:49], v[216:217] op_sel:[0,0,1] op_sel_hi:[0,1,1]
	v_pk_fma_f32 v[68:69], v[214:215], s[50:51], v[216:217] op_sel:[0,0,1] op_sel_hi:[0,1,1]
	v_pk_fma_f32 v[70:71], v[214:215], s[58:59], v[216:217] op_sel:[0,0,1] op_sel_hi:[0,1,1]
	v_pk_fma_f32 v[72:73], v[214:215], s[64:65], v[216:217] op_sel:[0,0,1] op_sel_hi:[0,1,1]
	v_pk_fma_f32 v[74:75], v[214:215], s[80:81], v[216:217] op_sel:[0,0,1] op_sel_hi:[0,1,1]
	v_pk_fma_f32 v[76:77], v[214:215], s[82:83], v[216:217] op_sel:[0,0,1] op_sel_hi:[0,1,1]
	v_pk_fma_f32 v[78:79], v[214:215], s[14:15], v[216:217] op_sel:[0,0,1] op_sel_hi:[1,1,0]
	v_mul_f32_e32 v83, 0x41d80000, v214
	v_mov_b32_e32 v216, v179
	v_pk_add_f32 v[94:95], v[216:217], v[82:83] op_sel_hi:[0,1]
	v_pk_add_f32 v[80:81], v[216:217], v[80:81] op_sel_hi:[0,1]
	v_pk_fma_f32 v[92:93], v[214:215], s[82:83], v[216:217] op_sel_hi:[0,1,0]
	v_pk_fma_f32 v[90:91], v[214:215], s[80:81], v[216:217] op_sel_hi:[0,1,0]
	v_pk_fma_f32 v[88:89], v[214:215], s[64:65], v[216:217] op_sel_hi:[0,1,0]
	v_pk_fma_f32 v[86:87], v[214:215], s[58:59], v[216:217] op_sel_hi:[0,1,0]
	v_pk_fma_f32 v[84:85], v[214:215], s[50:51], v[216:217] op_sel_hi:[0,1,0]
	v_pk_fma_f32 v[82:83], v[214:215], s[48:49], v[216:217] op_sel_hi:[0,1,0]
	v_fmac_f32_e32 v217, 0x41d80000, v214
	v_mov_b32_e32 v79, v217
	s_branch .Lattn_i2_done

; #define SBAR() __builtin_amdgcn_sched_barrier(0)
; #define SLOADA(k0) do { vsA0 = *(const bf16x8*)(&Vh[(size_t)((k0) + sr) * LDP + sc]); vsA1 = *(const bf16x8*)(&Vh[(size_t)((k0) + 32 + sr) * LDP + sc]); \
;     ksA0 = *(const bf16x8*)(&Kh[(size_t)((k0) + sr) * LDP + sc]); ksA1 = *(const bf16x8*)(&Kh[(size_t)((k0) + 32 + sr) * LDP + sc]); } while (0)
; #define SWRITEA(b) do { *(bf16x8*)(V_lds + (b) * SHM_V + vst0) = vsA0; *(bf16x8*)(V_lds + (b) * SHM_V + vst1) = vsA1; const int kc = sc * 2; \
;     *(bf16x8*)(K_lds + (b) * SHM_K + KSWZ(sr, kc)) = ksA0; *(bf16x8*)(K_lds + (b) * SHM_K + KSWZ(32 + sr, kc)) = ksA1; } while (0)
; #define SWAIT() asm volatile("s_waitcnt vmcnt(4)" ::: "memory")
; __device__ __forceinline__ void attn_unit(const bf16* __restrict__ P, bf16* __restrict__ MIXIN, const float* __restrict__ gn, int seq0, int h, int q0, int nt, float kmax0, float kmax1, float slope, float lam, char* lds) {
;     ...
;     __syncthreads(); SWAIT(); SWRITEA(0); __syncthreads();
;     if (j + 3 < t1) SLOADA((j + 3) * 64); SBAR();
;     sc_init(pA0, pA1, DQ(j + 1), nsl2, m_reg, SIDE(j + 1)); SBAR();
;     qk_fin(pA0, pA1, K_lds, qr, r32, hi, cbase, pB0, pB1, l_reg, pa0, pa1, pa2, pa3);
;     pv_exp(o, vb0 + SHM_V, pa0, pa1, pa2, pa3, pA0, pA1);
.Lattn_i2_done:
	s_add_i32 s76, s33, 2
	s_barrier
	s_waitcnt vmcnt(4)
	s_cmp_ge_i32 s76, s3
	s_cselect_b64 s[0:1], -1, 0
	s_and_b64 vcc, exec, s[0:1]
	ds_write_b128 v239, v[144:147]
	ds_write_b128 v240, v[152:155]
	ds_write_b128 v237, v[148:151] offset:32768
	ds_write_b128 v238, v[156:159] offset:32768
	s_waitcnt lgkmcnt(0)
	s_barrier
	s_cbranch_vccnz .LBB0_328
	v_subrev_u32_e32 v214, 32, v246
	v_mad_i64_i32 v[214:215], vcc, v214, s27, 0
	v_or_b32_e32 v214, v214, v185
	v_mad_i64_i32 v[216:217], vcc, v246, s27, 0
	v_lshl_add_u64 v[214:215], v[214:215], 1, s[24:25]
	v_or_b32_e32 v216, v216, v185
	v_lshl_add_u64 v[216:217], v[216:217], 1, s[24:25]
	global_load_dwordx4 v[144:147], v[214:215], off offset:2048
	global_load_dwordx4 v[148:151], v[214:215], off offset:1024
	global_load_dwordx4 v[152:155], v[216:217], off offset:2048
	global_load_dwordx4 v[156:159], v[216:217], off offset:1024
.LBB0_328:
.LBB0_331:
	v_add_f32_e32 v179, v247, v248
	v_add_f32_e32 v179, v231, v179
	ds_read_b128 v[214:217], v241 offset:32768
	ds_read_b128 v[248:251], v241 offset:40960
	v_add_f32_e32 v181, 0, v112
	v_add_f32_e32 v181, v113, v181
	v_cvt_pk_bf16_f32 v112, v112, v113
	v_add_f32_e32 v181, v114, v181
	v_add_f32_e32 v181, v115, v181
	v_cvt_pk_bf16_f32 v113, v114, v115
	v_add_f32_e32 v181, v116, v181
	v_add_f32_e32 v181, v117, v181
	v_cvt_pk_bf16_f32 v114, v116, v117
	v_add_f32_e32 v181, v118, v181
	v_add_f32_e32 v181, v119, v181
	v_cvt_pk_bf16_f32 v115, v118, v119
	s_nop 1
	v_permlane32_swap_b32_e32 v112, v114
	v_permlane32_swap_b32_e32 v113, v115
	s_waitcnt lgkmcnt(1)
	v_mfma_f32_32x32x16_bf16 v[80:95], v[214:217], v[132:135], v[80:95]
	s_waitcnt lgkmcnt(0)
	v_mfma_f32_32x32x16_bf16 v[64:79], v[248:251], v[132:135], v[64:79]
	ds_read_b128 v[214:217], v242 offset:32768
	ds_read_b128 v[248:251], v242 offset:40960
	v_add_f32_e32 v181, v120, v181
	v_add_f32_e32 v181, v121, v181
	v_cvt_pk_bf16_f32 v116, v120, v121
	v_add_f32_e32 v181, v122, v181
	v_add_f32_e32 v181, v123, v181
	v_cvt_pk_bf16_f32 v117, v122, v123
	v_add_f32_e32 v181, v124, v181
	v_add_f32_e32 v181, v125, v181
	v_cvt_pk_bf16_f32 v118, v124, v125
	v_add_f32_e32 v181, v126, v181
	v_add_f32_e32 v181, v127, v181
	v_cvt_pk_bf16_f32 v119, v126, v127
	s_nop 1
	v_permlane32_swap_b32_e32 v116, v118
	v_permlane32_swap_b32_e32 v117, v119
	s_waitcnt lgkmcnt(1)
	v_mfma_f32_32x32x16_bf16 v[80:95], v[214:217], v[128:131], v[80:95]
	s_waitcnt lgkmcnt(0)
	v_mfma_f32_32x32x16_bf16 v[64:79], v[248:251], v[128:131], v[64:79]
	ds_read_b128 v[214:217], v243 offset:32768
	ds_read_b128 v[248:251], v243 offset:40960
	v_add_f32_e32 v181, v96, v181
	v_add_f32_e32 v181, v97, v181
	v_cvt_pk_bf16_f32 v96, v96, v97
	v_add_f32_e32 v181, v98, v181
	v_add_f32_e32 v181, v99, v181
	v_cvt_pk_bf16_f32 v97, v98, v99
	v_add_f32_e32 v181, v100, v181
	v_add_f32_e32 v181, v101, v181
	v_cvt_pk_bf16_f32 v98, v100, v101
	v_add_f32_e32 v181, v102, v181
	v_add_f32_e32 v181, v103, v181
	v_cvt_pk_bf16_f32 v99, v102, v103
	s_nop 1
	v_permlane32_swap_b32_e32 v96, v98
	v_permlane32_swap_b32_e32 v97, v99
	s_waitcnt lgkmcnt(1)
	v_mfma_f32_32x32x16_bf16 v[80:95], v[214:217], v[140:143], v[80:95]
	s_waitcnt lgkmcnt(0)
	v_mfma_f32_32x32x16_bf16 v[64:79], v[248:251], v[140:143], v[64:79]
	ds_read_b128 v[214:217], v244 offset:32768
	ds_read_b128 v[248:251], v244 offset:40960
	v_add_f32_e32 v181, v104, v181
	v_add_f32_e32 v181, v105, v181
	v_cvt_pk_bf16_f32 v100, v104, v105
	v_add_f32_e32 v181, v106, v181
	v_add_f32_e32 v181, v107, v181
	v_cvt_pk_bf16_f32 v101, v106, v107
	v_add_f32_e32 v181, v108, v181
	v_add_f32_e32 v181, v109, v181
	v_cvt_pk_bf16_f32 v102, v108, v109
	v_add_f32_e32 v181, v110, v181
	v_add_f32_e32 v120, v111, v181
	v_cvt_pk_bf16_f32 v103, v110, v111
	s_nop 1
	v_permlane32_swap_b32_e32 v100, v102
	v_permlane32_swap_b32_e32 v101, v103
	v_mov_b32_e32 v104, v120
	s_nop 1
	v_permlane32_swap_b32_e32 v120, v104
	v_add_f32_e32 v104, v120, v104
	v_add_f32_e32 v231, v179, v104
	s_waitcnt lgkmcnt(1)
	v_mfma_f32_32x32x16_bf16 v[80:95], v[214:217], v[136:139], v[80:95]
	s_waitcnt lgkmcnt(0)
	v_mfma_f32_32x32x16_bf16 v[64:79], v[248:251], v[136:139], v[64:79]
	s_nop 0
	ds_read_b64_tr_b16 v[104:105], v245 offset:0
	ds_read_b64_tr_b16 v[106:107], v245 offset:2048
	ds_read_b64_tr_b16 v[108:109], v245 offset:4096
	ds_read_b64_tr_b16 v[110:111], v245 offset:6144
	ds_read_b64_tr_b16 v[120:121], v245 offset:8192
	ds_read_b64_tr_b16 v[122:123], v245 offset:10240
	ds_read_b64_tr_b16 v[124:125], v245 offset:12288
	ds_read_b64_tr_b16 v[126:127], v245 offset:14336
	s_waitcnt lgkmcnt(4)
	v_mfma_f32_32x32x16_bf16 v[48:63], v[112:115], v[104:107], v[48:63]
	v_exp_f32_e32 v80, v80
	v_exp_f32_e32 v81, v81
	v_mfma_f32_32x32x16_bf16 v[48:63], v[116:119], v[108:111], v[48:63]
	ds_read_b64_tr_b16 v[104:105], v245 offset:512
	ds_read_b64_tr_b16 v[106:107], v245 offset:2560
	ds_read_b64_tr_b16 v[108:109], v245 offset:4608
	ds_read_b64_tr_b16 v[110:111], v245 offset:6656
	v_exp_f32_e32 v82, v82
	v_exp_f32_e32 v83, v83
	s_waitcnt lgkmcnt(4)
; #define SBAR() __builtin_amdgcn_sched_barrier(0)
; __device__ __forceinline__ void sc_init(f32x16& p0, f32x16& p1, float dq, float nsl2, float m_ref, int side) {
;   if (side != 0) { const float sg = (float)side; const float base0 = fmaf(sg * nsl2, dq, -m_ref), base1 = base0 - sg * 32.f * nsl2;
; #pragma unroll
;     for (int r = 0; r < 16; ++r) { const float c = -sg * nsl2 * (float)((r & 3) + 8 * (r >> 2)); p0[r] = base0 + c; p1[r] = base1 + c; }
;   } else {
; __device__ __forceinline__ void pv_exp(f32x16* o, int vb, bf16x8 pa0, bf16x8 pa1, bf16x8 pa2, bf16x8 pa3, f32x16& n0, f32x16& n1) {
;     ...
; #pragma unroll
;   for (int r = 8; r < 16; ++r) n1[r] = __builtin_amdgcn_exp2f(n1[r]);
;   asm volatile("" : "+v"(n1)); SBAR();
; }
	v_mfma_f32_32x32x16_bf16 v[48:63], v[96:99], v[120:123], v[48:63]
	v_exp_f32_e32 v84, v84
	v_exp_f32_e32 v85, v85
	v_mfma_f32_32x32x16_bf16 v[48:63], v[100:103], v[124:127], v[48:63]
	ds_read_b64_tr_b16 v[120:121], v245 offset:8704
	ds_read_b64_tr_b16 v[122:123], v245 offset:10752
	ds_read_b64_tr_b16 v[124:125], v245 offset:12800
	ds_read_b64_tr_b16 v[126:127], v245 offset:14848
	v_exp_f32_e32 v86, v86
	v_exp_f32_e32 v87, v87
	s_waitcnt lgkmcnt(4)
	v_mfma_f32_32x32x16_bf16 v[32:47], v[112:115], v[104:107], v[32:47]
	v_exp_f32_e32 v88, v88
	v_exp_f32_e32 v89, v89
	v_mfma_f32_32x32x16_bf16 v[32:47], v[116:119], v[108:111], v[32:47]
	ds_read_b64_tr_b16 v[104:105], v245 offset:1024
	ds_read_b64_tr_b16 v[106:107], v245 offset:3072
	ds_read_b64_tr_b16 v[108:109], v245 offset:5120
	ds_read_b64_tr_b16 v[110:111], v245 offset:7168
	v_exp_f32_e32 v90, v90
	v_exp_f32_e32 v91, v91
	s_waitcnt lgkmcnt(4)
	v_mfma_f32_32x32x16_bf16 v[32:47], v[96:99], v[120:123], v[32:47]
	v_exp_f32_e32 v92, v92
	v_exp_f32_e32 v93, v93
	v_mfma_f32_32x32x16_bf16 v[32:47], v[100:103], v[124:127], v[32:47]
	ds_read_b64_tr_b16 v[120:121], v245 offset:9216
	ds_read_b64_tr_b16 v[122:123], v245 offset:11264
	ds_read_b64_tr_b16 v[124:125], v245 offset:13312
	ds_read_b64_tr_b16 v[126:127], v245 offset:15360
	v_exp_f32_e32 v94, v94
	v_exp_f32_e32 v95, v95
	s_waitcnt lgkmcnt(4)
	v_mfma_f32_32x32x16_bf16 v[16:31], v[112:115], v[104:107], v[16:31]
	v_exp_f32_e32 v64, v64
	v_exp_f32_e32 v65, v65
	v_mfma_f32_32x32x16_bf16 v[16:31], v[116:119], v[108:111], v[16:31]
	ds_read_b64_tr_b16 v[104:105], v245 offset:1536
	ds_read_b64_tr_b16 v[106:107], v245 offset:3584
	ds_read_b64_tr_b16 v[108:109], v245 offset:5632
	ds_read_b64_tr_b16 v[110:111], v245 offset:7680
	v_exp_f32_e32 v66, v66
	v_exp_f32_e32 v67, v67
	s_waitcnt lgkmcnt(4)
	v_mfma_f32_32x32x16_bf16 v[16:31], v[96:99], v[120:123], v[16:31]
	v_exp_f32_e32 v68, v68
	v_exp_f32_e32 v69, v69
	v_mfma_f32_32x32x16_bf16 v[16:31], v[100:103], v[124:127], v[16:31]
	ds_read_b64_tr_b16 v[120:121], v245 offset:9728
	ds_read_b64_tr_b16 v[122:123], v245 offset:11776
	ds_read_b64_tr_b16 v[124:125], v245 offset:13824
	ds_read_b64_tr_b16 v[126:127], v245 offset:15872
	v_exp_f32_e32 v70, v70
	v_exp_f32_e32 v71, v71
	s_waitcnt lgkmcnt(4)
	v_mfma_f32_32x32x16_bf16 v[0:15], v[112:115], v[104:107], v[0:15]
	v_exp_f32_e32 v72, v72
	v_exp_f32_e32 v73, v73
	v_mfma_f32_32x32x16_bf16 v[0:15], v[116:119], v[108:111], v[0:15]
	v_exp_f32_e32 v74, v74
	v_exp_f32_e32 v75, v75
	s_waitcnt lgkmcnt(0)
	v_mfma_f32_32x32x16_bf16 v[0:15], v[96:99], v[120:123], v[0:15]
	v_exp_f32_e32 v76, v76
	v_exp_f32_e32 v77, v77
	v_mfma_f32_32x32x16_bf16 v[0:15], v[100:103], v[124:127], v[0:15]
	v_exp_f32_e32 v78, v78
	v_exp_f32_e32 v79, v79
	s_add_i32 s6, s76, -1
	s_cmp_gt_u32 s6, s73
	v_cvt_f32_i32_e32 v97, s6
	s_cselect_b64 s[98:99], -1, 0
	s_cmp_ge_u32 s6, s72
	v_cndmask_b32_e64 v96, 0, -1, s[98:99]
	s_cselect_b64 vcc, -1, 0
	v_cndmask_b32_e32 v96, 1, v96, vcc
	v_cmp_ne_u32_e32 vcc, 0, v96
	v_fmamk_f32 v208, v97, 0xc2800000, v184
	s_cbranch_vccz .Lattn_i1_ovl
	v_cvt_f32_i32_e32 v96, v96
	v_mul_f32_e32 v98, v180, v96
	v_mul_f32_e32 v97, 0x42000000, v96
	v_xor_b32_e32 v96, 0x80000000, v96
	v_fma_f32 v179, v98, v208, -v182
	v_pk_mul_f32 v[214:215], v[188:189], v[96:97]
	v_pk_fma_f32 v[216:217], v[188:189], v[96:97], v[178:179] neg_lo:[1,0,0] neg_hi:[1,0,0]
	v_mul_f32_e32 v112, 0, v214
	v_pk_mul_f32 v[114:115], v[214:215], s[14:15]
	v_mov_b32_e32 v113, v214
	v_pk_add_f32 v[96:97], v[112:113], v[216:217] op_sel:[0,1]
	v_pk_fma_f32 v[98:99], v[214:215], s[48:49], v[216:217] op_sel:[0,0,1] op_sel_hi:[0,1,1]
	v_pk_fma_f32 v[100:101], v[214:215], s[50:51], v[216:217] op_sel:[0,0,1] op_sel_hi:[0,1,1]
	v_pk_fma_f32 v[102:103], v[214:215], s[58:59], v[216:217] op_sel:[0,0,1] op_sel_hi:[0,1,1]
	v_pk_fma_f32 v[104:105], v[214:215], s[64:65], v[216:217] op_sel:[0,0,1] op_sel_hi:[0,1,1]
	v_pk_fma_f32 v[106:107], v[214:215], s[80:81], v[216:217] op_sel:[0,0,1] op_sel_hi:[0,1,1]
	v_pk_fma_f32 v[108:109], v[214:215], s[82:83], v[216:217] op_sel:[0,0,1] op_sel_hi:[0,1,1]
	v_pk_fma_f32 v[110:111], v[214:215], s[14:15], v[216:217] op_sel:[0,0,1] op_sel_hi:[1,1,0]
	v_mul_f32_e32 v115, 0x41d80000, v214
	v_mov_b32_e32 v216, v179
	v_pk_add_f32 v[126:127], v[216:217], v[114:115] op_sel_hi:[0,1]
	v_pk_add_f32 v[112:113], v[216:217], v[112:113] op_sel_hi:[0,1]
	v_pk_fma_f32 v[124:125], v[214:215], s[82:83], v[216:217] op_sel_hi:[0,1,0]
	v_pk_fma_f32 v[122:123], v[214:215], s[80:81], v[216:217] op_sel_hi:[0,1,0]
	v_pk_fma_f32 v[120:121], v[214:215], s[64:65], v[216:217] op_sel_hi:[0,1,0]
	v_pk_fma_f32 v[118:119], v[214:215], s[58:59], v[216:217] op_sel_hi:[0,1,0]
	v_pk_fma_f32 v[116:117], v[214:215], s[50:51], v[216:217] op_sel_hi:[0,1,0]
	v_pk_fma_f32 v[114:115], v[214:215], s[48:49], v[216:217] op_sel_hi:[0,1,0]
	v_fmac_f32_e32 v217, 0x41d80000, v214
	v_mov_b32_e32 v111, v217
	s_branch .Lattn_i1_done

; #define SBAR() __builtin_amdgcn_sched_barrier(0)
; #define SLOADB(k0) do { vsB0 = *(const bf16x8*)(&Vh[(size_t)((k0) + sr) * LDP + sc]); vsB1 = *(const bf16x8*)(&Vh[(size_t)((k0) + 32 + sr) * LDP + sc]); \
;     ksB0 = *(const bf16x8*)(&Kh[(size_t)((k0) + sr) * LDP + sc]); ksB1 = *(const bf16x8*)(&Kh[(size_t)((k0) + 32 + sr) * LDP + sc]); } while (0)
; #define SWRITEB(b) do { *(bf16x8*)(V_lds + (b) * SHM_V + vst0) = vsB0; *(bf16x8*)(V_lds + (b) * SHM_V + vst1) = vsB1; const int kc = sc * 2; \
;     *(bf16x8*)(K_lds + (b) * SHM_K + KSWZ(sr, kc)) = ksB0; *(bf16x8*)(K_lds + (b) * SHM_K + KSWZ(32 + sr, kc)) = ksB1; } while (0)
; #define SWAIT() asm volatile("s_waitcnt vmcnt(4)" ::: "memory")
; __device__ __forceinline__ void attn_unit(const bf16* __restrict__ P, bf16* __restrict__ MIXIN, const float* __restrict__ gn, int seq0, int h, int q0, int nt, float kmax0, float kmax1, float slope, float lam, char* lds) {
;     ...
;     if (j + 2 < t1) SLOADB((j + 2) * 64); SBAR();
;     ...
;     __syncthreads(); SWAIT(); SWRITEB(1); __syncthreads();
;   }
.Lattn_i1_done:
	s_barrier
	s_waitcnt vmcnt(4)
	v_add_u32_e32 v246, 0x80, v246
	s_and_b64 vcc, exec, s[0:1]
	s_waitcnt vmcnt(3)
	ds_write_b128 v239, v[160:163] offset:16384
	s_waitcnt vmcnt(1)
	ds_write_b128 v240, v[168:171] offset:16384
	ds_write_b128 v237, v[164:167] offset:49152
	s_waitcnt vmcnt(0)
	ds_write_b128 v238, v[172:175] offset:49152
	s_waitcnt lgkmcnt(0)
	s_barrier
	s_cbranch_vccnz .LBB0_336
	s_mov_b32 s33, s76
	s_add_i32 s0, s33, 1
	s_cmp_ge_i32 s0, s3
	s_cbranch_scc1 .LBB0_326
	v_add_u32_e32 v214, 0xffffffa0, v246
	v_mad_i64_i32 v[214:215], s[0:1], v214, s27, 0
	v_subrev_u32_e32 v216, 64, v246
	v_or_b32_e32 v214, v214, v185
	v_mad_i64_i32 v[216:217], s[0:1], v216, s27, 0
	v_lshl_add_u64 v[214:215], v[214:215], 1, s[24:25]
	v_or_b32_e32 v216, v216, v185
	v_lshl_add_u64 v[216:217], v[216:217], 1, s[24:25]
	global_load_dwordx4 v[160:163], v[214:215], off offset:2048
	global_load_dwordx4 v[164:167], v[214:215], off offset:1024
	global_load_dwordx4 v[168:171], v[216:217], off offset:2048
	global_load_dwordx4 v[172:175], v[216:217], off offset:1024
	s_branch .LBB0_326
